# on top of early buffer_inv: non-leader workgroups poll TOPGEN directly, leaders no longer bump XGEN (in-loop seams)
# speedup vs baseline: 1.0110x; 1.0024x over previous
.LBB0_380:
	s_or_b64 exec, exec, s[10:11]
	v_cvt_f32_u32_e32 v6, v4
	s_waitcnt vmcnt(0)
	v_readfirstlane_b32 s10, v5
	v_sub_u32_e32 v5, 0, v4
	v_rcp_iflag_f32_e32 v6, v6
	v_add_u32_e32 v7, s10, v3
	v_mul_f32_e32 v6, 0x4f7ffffe, v6
	v_cvt_u32_f32_e32 v6, v6
	v_mul_lo_u32 v3, v5, v6
	v_mul_hi_u32 v3, v6, v3
	v_add_u32_e32 v3, v6, v3
	v_mul_hi_u32 v3, v7, v3
	v_mul_lo_u32 v5, v3, v4
	v_sub_u32_e32 v5, v7, v5
	v_add_u32_e32 v6, 1, v3
	v_cmp_ge_u32_e32 vcc, v5, v4
	s_nop 1
	v_cndmask_b32_e32 v3, v3, v6, vcc
	v_sub_u32_e32 v6, v5, v4
	v_cndmask_b32_e32 v5, v5, v6, vcc
	v_add_u32_e32 v6, 1, v3
	v_cmp_ge_u32_e32 vcc, v5, v4
	v_add_u32_e32 v5, 1, v7
	s_nop 0
	v_cndmask_b32_e32 v3, v3, v6, vcc
	v_mul_lo_u32 v6, v4, v3
	v_add_u32_e32 v4, v6, v4
	v_cmp_ne_u32_e32 vcc, v5, v4
	s_and_saveexec_b64 s[10:11], vcc
	s_xor_b64 s[10:11], exec, s[10:11]
	s_cbranch_execz .LBB0_394
	v_readlane_b32 s14, v244, 1
	v_readlane_b32 s15, v244, 2
	s_waitcnt lgkmcnt(0)
	s_nop 3
	global_load_dword v2, v173, s[14:15] sc1
	s_waitcnt vmcnt(0)
	v_cmp_eq_u32_e32 vcc, v2, v3
	s_and_saveexec_b64 s[14:15], vcc
	s_cbranch_execz .LBB0_393
	s_mov_b32 s39, 1
	s_mov_b64 s[18:19], 0
	s_branch .LBB0_384

.LBB0_386:
	v_readlane_b32 s22, v244, 1
	v_readlane_b32 s23, v244, 2
	s_add_i32 s39, s39, 1
	s_mov_b64 s[28:29], -1
	s_nop 2
	global_load_dword v2, v173, s[22:23] sc1
	s_waitcnt vmcnt(0)
	v_cmp_ne_u32_e32 vcc, v2, v3
	s_orn2_b64 s[22:23], vcc, exec
	s_branch .LBB0_383

.LBB0_411:
	s_or_b64 exec, exec, s[10:11]
	s_mov_b64 s[10:11], exec
	v_mbcnt_lo_u32_b32 v2, s10, 0
	v_mbcnt_hi_u32_b32 v2, s11, v2
	v_cmp_eq_u32_e32 vcc, 0, v2
	s_waitcnt vmcnt(0)
	s_and_saveexec_b64 s[14:15], vcc
	s_cbranch_execz .LBB0_413
	s_bcnt1_i32_b64 s10, s[10:11]
	v_mov_b32_e32 v2, s10
	v_readlane_b32 s10, v245, 61
	v_readlane_b32 s11, v245, 62
	s_nop 4
	s_nop 0

.LBB0_1447:
	s_or_b64 exec, exec, s[10:11]
	v_cvt_f32_u32_e32 v6, v4
	s_waitcnt vmcnt(0)
	v_readfirstlane_b32 s10, v5
	v_sub_u32_e32 v5, 0, v4
	v_rcp_iflag_f32_e32 v6, v6
	v_add_u32_e32 v7, s10, v3
	v_mul_f32_e32 v6, 0x4f7ffffe, v6
	v_cvt_u32_f32_e32 v6, v6
	v_mul_lo_u32 v3, v5, v6
	v_mul_hi_u32 v3, v6, v3
	v_add_u32_e32 v3, v6, v3
	v_mul_hi_u32 v3, v7, v3
	v_mul_lo_u32 v5, v3, v4
	v_sub_u32_e32 v5, v7, v5
	v_add_u32_e32 v6, 1, v3
	v_cmp_ge_u32_e32 vcc, v5, v4
	s_nop 1
	v_cndmask_b32_e32 v3, v3, v6, vcc
	v_sub_u32_e32 v6, v5, v4
	v_cndmask_b32_e32 v5, v5, v6, vcc
	v_add_u32_e32 v6, 1, v3
	v_cmp_ge_u32_e32 vcc, v5, v4
	v_add_u32_e32 v5, 1, v7
	s_nop 0
	v_cndmask_b32_e32 v3, v3, v6, vcc
	v_mul_lo_u32 v6, v4, v3
	v_add_u32_e32 v4, v6, v4
	v_cmp_ne_u32_e32 vcc, v5, v4
	s_and_saveexec_b64 s[10:11], vcc
	s_xor_b64 s[10:11], exec, s[10:11]
	s_cbranch_execz .LBB0_1461
	v_readlane_b32 s14, v244, 1
	v_readlane_b32 s15, v244, 2
	s_waitcnt lgkmcnt(0)
	s_nop 3
	global_load_dword v2, v173, s[14:15] sc1
	s_waitcnt vmcnt(0)
	v_cmp_eq_u32_e32 vcc, v2, v3
	s_and_saveexec_b64 s[14:15], vcc
	s_cbranch_execz .LBB0_1460
	s_mov_b32 s38, 1
	s_mov_b64 s[18:19], 0
	s_branch .LBB0_1451

.LBB0_1453:
	v_readlane_b32 s22, v244, 1
	v_readlane_b32 s23, v244, 2
	s_add_i32 s38, s38, 1
	s_mov_b64 s[28:29], -1
	s_nop 2
	global_load_dword v2, v173, s[22:23] sc1
	s_waitcnt vmcnt(0)
	v_cmp_ne_u32_e32 vcc, v2, v3
	s_orn2_b64 s[22:23], vcc, exec
	s_branch .LBB0_1450

.LBB0_1479:
	s_bcnt1_i32_b64 s10, s[10:11]
	v_mov_b32_e32 v2, s10
	v_readlane_b32 s10, v245, 61
	v_readlane_b32 s11, v245, 62
	s_nop 4
	s_nop 0
	s_getpc_b64 s[98:99]
